# phase-0 weight transposes hand-written with batched loads, layer-0 weights only; layer-1 weight transposes moved to the end of layer 0's out-projection phase on workgroups >= 64 (idle there while 0..6
# speedup vs baseline: 1.0024x; 1.0024x over previous
.LBB0_33:
	s_load_dwordx2 s[24:25], s[0:1], 0x38
	s_load_dwordx2 s[26:27], s[0:1], 0x78
	s_waitcnt lgkmcnt(0)
	v_lshl_add_u32 v82, v23, 11, v2
	s_mov_b32 s23, s96
	s_movk_i32 s4, 0x2c0
	s_cmpk_lt_u32 s23, 0x2c0
	s_cselect_b32 s4, 0x0, s4
	s_add_i32 s23, s23, s4
	s_cmpk_gt_i32 s23, 0x57f
	s_cbranch_scc1 .Lpb_out0
	s_mul_hi_i32 s4, s23, 0x2e8ba2e9
	s_ashr_i32 s4, s4, 7
	s_mul_i32 s6, s4, 0x2c0
	s_sub_i32 s6, s23, s6
	s_mul_i32 s7, s6, 0xba3
	s_lshr_b32 s7, s7, 17
	s_mul_i32 s8, s7, 44
	s_sub_i32 s6, s6, s8
	s_mul_i32 s8, s4, 0xb00000
	s_mul_i32 s9, s7, 0xb0000
	s_add_u32 s8, s8, s9
	s_lshl_b32 s9, s6, 8
	s_add_u32 s8, s8, s9
	s_add_u32 s36, s24, s8
	s_addc_u32 s37, s25, 0
	s_sub_i32 s9, s6, 20
	s_cmp_gt_u32 s9, 15
	s_cbranch_scc1 .Lpb_nr0
	s_and_b32 s16, s6, 3
	s_lshr_b32 s9, s9, 2
	s_lshl_b32 s9, s9, 3
	s_lshr_b32 s9, 0x1d15141c, s9
	s_and_b32 s9, s9, 0xff
	s_lshl_b32 s16, s16, 1
	s_add_i32 s6, s9, s16
.Lpb_nr0:
	s_mul_i32 s8, s4, 0x580000
	s_lshl_b32 s9, s6, 17
	s_add_u32 s8, s8, s9
	s_lshl_b32 s9, s7, 7
	s_add_u32 s8, s8, s9
	s_add_u32 s38, s21, s8
	s_addc_u32 s39, s22, 0
	s_movk_i32 s40, 0x2c00
	s_branch .Lpb_dec0
.Lpb_out0:
	s_add_i32 s6, s23, 0xfffffa80
	s_lshr_b32 s4, s6, 8
	s_bfe_u32 s7, s6, 0x40004
	s_and_b32 s6, s6, 15
	s_lshl_b32 s8, s4, 22
	s_lshl_b32 s9, s7, 18
	s_add_u32 s8, s8, s9
	s_lshl_b32 s9, s6, 8
	s_add_u32 s8, s8, s9
	s_add_u32 s36, s26, s8
	s_addc_u32 s37, s27, 0
	s_lshl_b32 s8, s4, 21
	s_lshl_b32 s9, s6, 17
	s_add_u32 s8, s8, s9
	s_lshl_b32 s9, s7, 7
	s_add_u32 s8, s8, s9
	s_add_u32 s38, s19, s8
	s_addc_u32 s39, s20, 0
	s_movk_i32 s40, 0x1000
.Lpb_dec0:
	v_mad_u32_u24 v72, v22, s40, v0
	s_lshl_b32 s17, s40, 4
	global_load_dwordx4 v[4:7], v72, s[36:37] nt
	s_add_u32 s36, s36, s17
	s_addc_u32 s37, s37, 0
	global_load_dwordx4 v[8:11], v72, s[36:37] nt
	s_add_u32 s36, s36, s17
	s_addc_u32 s37, s37, 0
	global_load_dwordx4 v[12:15], v72, s[36:37] nt
	s_add_u32 s36, s36, s17
	s_addc_u32 s37, s37, 0
	global_load_dwordx4 v[16:19], v72, s[36:37] nt
	s_add_i32 s23, s96, 0x200
	s_cmpk_gt_u32 s23, 0x3bf
	s_cbranch_scc1 .Lpb_dummy
	s_movk_i32 s4, 0x2c0
	s_cmpk_lt_u32 s23, 0x2c0
	s_cselect_b32 s4, 0x0, s4
	s_add_i32 s23, s23, s4
	s_cmpk_gt_i32 s23, 0x57f
	s_cbranch_scc1 .Lpb_out1
	s_mul_hi_i32 s4, s23, 0x2e8ba2e9
	s_ashr_i32 s4, s4, 7
	s_mul_i32 s6, s4, 0x2c0
	s_sub_i32 s6, s23, s6
	s_mul_i32 s7, s6, 0xba3
	s_lshr_b32 s7, s7, 17
	s_mul_i32 s8, s7, 44
	s_sub_i32 s6, s6, s8
	s_mul_i32 s8, s4, 0xb00000
	s_mul_i32 s9, s7, 0xb0000
	s_add_u32 s8, s8, s9
	s_lshl_b32 s9, s6, 8
	s_add_u32 s8, s8, s9
	s_add_u32 s42, s24, s8
	s_addc_u32 s43, s25, 0
	s_sub_i32 s9, s6, 20
	s_cmp_gt_u32 s9, 15
	s_cbranch_scc1 .Lpb_nr1
	s_and_b32 s16, s6, 3
	s_lshr_b32 s9, s9, 2
	s_lshl_b32 s9, s9, 3
	s_lshr_b32 s9, 0x1d15141c, s9
	s_and_b32 s9, s9, 0xff
	s_lshl_b32 s16, s16, 1
	s_add_i32 s6, s9, s16
.Lpb_nr1:
	s_mul_i32 s8, s4, 0x580000
	s_lshl_b32 s9, s6, 17
	s_add_u32 s8, s8, s9
	s_lshl_b32 s9, s7, 7
	s_add_u32 s8, s8, s9
	s_add_u32 s44, s21, s8
	s_addc_u32 s45, s22, 0
	s_movk_i32 s41, 0x2c00
	s_branch .Lpb_dec1
.Lpb_out1:
	s_add_i32 s6, s23, 0xfffffa80
	s_lshr_b32 s4, s6, 8
	s_bfe_u32 s7, s6, 0x40004
	s_and_b32 s6, s6, 15
	s_lshl_b32 s8, s4, 22
	s_lshl_b32 s9, s7, 18
	s_add_u32 s8, s8, s9
	s_lshl_b32 s9, s6, 8
	s_add_u32 s8, s8, s9
	s_add_u32 s42, s26, s8
	s_addc_u32 s43, s27, 0
	s_lshl_b32 s8, s4, 21
	s_lshl_b32 s9, s6, 17
	s_add_u32 s8, s8, s9
	s_lshl_b32 s9, s7, 7
	s_add_u32 s8, s8, s9
	s_add_u32 s44, s19, s8
	s_addc_u32 s45, s20, 0
	s_movk_i32 s41, 0x1000
	s_branch .Lpb_dec1
.Lpb_dummy:
	s_mov_b32 s42, s24
	s_mov_b32 s43, s25
	s_movk_i32 s41, 0x2c00
	s_mov_b32 s4, 0
	s_branch .Lpb_ldl
.Lpb_dec1:
	s_mov_b32 s4, 1
.Lpb_ldl:
	v_mad_u32_u24 v73, v22, s41, v0
	s_lshl_b32 s17, s41, 4
	global_load_dwordx4 v[208:211], v73, s[42:43] nt
	s_add_u32 s42, s42, s17
	s_addc_u32 s43, s43, 0
	global_load_dwordx4 v[212:215], v73, s[42:43] nt
	s_add_u32 s42, s42, s17
	s_addc_u32 s43, s43, 0
	global_load_dwordx4 v[216:219], v73, s[42:43] nt
	s_add_u32 s42, s42, s17
	s_addc_u32 s43, s43, 0
	global_load_dwordx4 v[220:223], v73, s[42:43] nt
	s_barrier
	s_waitcnt vmcnt(7)
	ds_write2_b32 v25, v4, v5 offset1:1
	ds_write2_b32 v25, v6, v7 offset0:2 offset1:3
	s_waitcnt vmcnt(6)
	ds_write2_b32 v26, v8, v9 offset1:1
	ds_write2_b32 v27, v10, v11 offset1:1
	s_waitcnt vmcnt(5)
	ds_write2_b32 v28, v12, v13 offset1:1
	ds_write2_b32 v29, v14, v15 offset1:1
	s_waitcnt vmcnt(4)
	ds_write2_b32 v30, v16, v17 offset1:1
	ds_write2_b32 v31, v18, v19 offset1:1
	s_waitcnt lgkmcnt(0)
	s_barrier
	ds_read2_b32 v[4:5], v24 offset1:65
	ds_read2_b32 v[6:7], v24 offset0:130 offset1:195
	ds_read2_b32 v[8:9], v32 offset0:4 offset1:69
	ds_read2_b32 v[10:11], v32 offset0:134 offset1:199
	ds_read2_b32 v[12:13], v33 offset0:8 offset1:73
	ds_read2_b32 v[14:15], v33 offset0:138 offset1:203
	ds_read2_b32 v[16:17], v34 offset0:12 offset1:77
	ds_read2_b32 v[18:19], v34 offset0:142 offset1:207
	s_waitcnt lgkmcnt(7)
	v_cvt_pk_bf16_f32 v4, v4, v5
	s_waitcnt lgkmcnt(6)
	v_cvt_pk_bf16_f32 v5, v6, v7
	s_waitcnt lgkmcnt(5)
	v_cvt_pk_bf16_f32 v6, v8, v9
	s_waitcnt lgkmcnt(4)
	v_cvt_pk_bf16_f32 v7, v10, v11
	s_waitcnt lgkmcnt(3)
	v_cvt_pk_bf16_f32 v8, v12, v13
	s_waitcnt lgkmcnt(2)
	v_cvt_pk_bf16_f32 v9, v14, v15
	s_waitcnt lgkmcnt(1)
	v_cvt_pk_bf16_f32 v10, v16, v17
	s_waitcnt lgkmcnt(0)
	v_cvt_pk_bf16_f32 v11, v18, v19
	global_store_dwordx4 v82, v[4:7], s[38:39]
	global_store_dwordx4 v82, v[8:11], s[38:39] offset:16
	s_cmp_eq_u32 s4, 0
	s_cbranch_scc1 .Lpb_done
	s_barrier
	s_waitcnt vmcnt(5)
	ds_write2_b32 v25, v208, v209 offset1:1
	ds_write2_b32 v25, v210, v211 offset0:2 offset1:3
	s_waitcnt vmcnt(4)
	ds_write2_b32 v26, v212, v213 offset1:1
	ds_write2_b32 v27, v214, v215 offset1:1
	s_waitcnt vmcnt(3)
	ds_write2_b32 v28, v216, v217 offset1:1
	ds_write2_b32 v29, v218, v219 offset1:1
	s_waitcnt vmcnt(2)
	ds_write2_b32 v30, v220, v221 offset1:1
	ds_write2_b32 v31, v222, v223 offset1:1
	s_waitcnt lgkmcnt(0)
	s_barrier
	ds_read2_b32 v[4:5], v24 offset1:65
	ds_read2_b32 v[6:7], v24 offset0:130 offset1:195
	ds_read2_b32 v[8:9], v32 offset0:4 offset1:69
	ds_read2_b32 v[10:11], v32 offset0:134 offset1:199
	ds_read2_b32 v[12:13], v33 offset0:8 offset1:73
	ds_read2_b32 v[14:15], v33 offset0:138 offset1:203
	ds_read2_b32 v[16:17], v34 offset0:12 offset1:77
	ds_read2_b32 v[18:19], v34 offset0:142 offset1:207
	s_waitcnt lgkmcnt(7)
	v_cvt_pk_bf16_f32 v4, v4, v5
	s_waitcnt lgkmcnt(6)
	v_cvt_pk_bf16_f32 v5, v6, v7
	s_waitcnt lgkmcnt(5)
	v_cvt_pk_bf16_f32 v6, v8, v9
	s_waitcnt lgkmcnt(4)
	v_cvt_pk_bf16_f32 v7, v10, v11
	s_waitcnt lgkmcnt(3)
	v_cvt_pk_bf16_f32 v8, v12, v13
	s_waitcnt lgkmcnt(2)
	v_cvt_pk_bf16_f32 v9, v14, v15
	s_waitcnt lgkmcnt(1)
	v_cvt_pk_bf16_f32 v10, v16, v17
	s_waitcnt lgkmcnt(0)
	v_cvt_pk_bf16_f32 v11, v18, v19
	global_store_dwordx4 v82, v[4:7], s[44:45]
	global_store_dwordx4 v82, v[8:11], s[44:45] offset:16
.Lpb_done:
	s_movk_i32 s23, 0x780
	s_load_dwordx16 s[36:51], s[0:1], 0x0

.LBB0_667:
	v_readlane_b32 s2, v205, 9
	v_readlane_b32 s3, v205, 10
	s_mov_b64 s[0:1], -1
	s_andn2_b64 vcc, exec, s[2:3]
	s_mov_b64 s[2:3], -1
	s_cbranch_vccnz .LBB0_178
	s_cmpk_lt_u32 s96, 64
	s_cbranch_scc1 .Lpo_skip
	s_sub_i32 s5, s96, 64
	v_readlane_b32 s24, v207, 18
	v_readlane_b32 s25, v207, 19
	v_readlane_b32 s26, v207, 34
	v_readlane_b32 s27, v207, 35
	s_add_u32 s28, s94, 0xd00000
	s_addc_u32 s29, s95, 0
	s_add_u32 s30, s94, 0x200000
	s_addc_u32 s31, s95, 0
	v_lshrrev_b32_e32 v22, 4, v138
	v_and_b32_e32 v0, 15, v138
	v_lshlrev_b32_e32 v0, 4, v0
	v_and_b32_e32 v2, 3, v138
	v_lshlrev_b32_e32 v24, 4, v2
	v_lshlrev_b32_e32 v2, 5, v2
	v_lshrrev_b32_e32 v23, 2, v138
	v_mul_u32_u24_e32 v24, 0x41, v24
	v_and_b32_e32 v25, -4, v138
	v_lshl_add_u32 v24, v24, 2, v25
	v_mul_u32_u24_e32 v25, 0x104, v22
	v_add_u32_e32 v25, v25, v0
	v_add_u32_e32 v26, 0x1040, v25
	v_add_u32_e32 v27, 0x1048, v25
	v_add_u32_e32 v28, 0x2080, v25
	v_add_u32_e32 v29, 0x2088, v25
	v_add_u32_e32 v30, 0x30c0, v25
	v_add_u32_e32 v31, 0x30c8, v25
	v_add_u32_e32 v83, 0x400, v24
	v_add_u32_e32 v84, 0x800, v24
	v_add_u32_e32 v85, 0xc00, v24
	v_lshl_add_u32 v82, v23, 11, v2
	s_mov_b32 s1, s5
	s_movk_i32 s86, 0x3c0
	s_cmpk_lt_u32 s1, 0x2c0
	s_cselect_b32 s86, 0x2c0, s86
	s_add_i32 s1, s1, s86
	s_cmpk_gt_i32 s1, 0x57f
	s_cbranch_scc1 .Lpo_out0
	s_mul_hi_i32 s86, s1, 0x2e8ba2e9
	s_ashr_i32 s86, s86, 7
	s_mul_i32 s87, s86, 0x2c0
	s_sub_i32 s87, s1, s87
	s_mul_i32 s88, s87, 0xba3
	s_lshr_b32 s88, s88, 17
	s_mul_i32 s89, s88, 44
	s_sub_i32 s87, s87, s89
	s_mul_i32 s89, s86, 0xb00000
	s_mul_i32 s90, s88, 0xb0000
	s_add_u32 s89, s89, s90
	s_lshl_b32 s90, s87, 8
	s_add_u32 s89, s89, s90
	s_add_u32 s76, s24, s89
	s_addc_u32 s77, s25, 0
	s_sub_i32 s90, s87, 20
	s_cmp_gt_u32 s90, 15
	s_cbranch_scc1 .Lpo_nr0
	s_and_b32 s91, s87, 3
	s_lshr_b32 s90, s90, 2
	s_lshl_b32 s90, s90, 3
	s_lshr_b32 s90, 0x1d15141c, s90
	s_and_b32 s90, s90, 0xff
	s_lshl_b32 s91, s91, 1
	s_add_i32 s87, s90, s91
.Lpo_nr0:
	s_mul_i32 s89, s86, 0x580000
	s_lshl_b32 s90, s87, 17
	s_add_u32 s89, s89, s90
	s_lshl_b32 s90, s88, 7
	s_add_u32 s89, s89, s90
	s_add_u32 s78, s30, s89
	s_addc_u32 s79, s31, 0
	s_movk_i32 s80, 0x2c00
	s_branch .Lpo_dec0
.Lpo_out0:
	s_add_i32 s87, s1, 0xfffffa80
	s_lshr_b32 s86, s87, 8
	s_bfe_u32 s88, s87, 0x40004
	s_and_b32 s87, s87, 15
	s_lshl_b32 s89, s86, 22
	s_lshl_b32 s90, s88, 18
	s_add_u32 s89, s89, s90
	s_lshl_b32 s90, s87, 8
	s_add_u32 s89, s89, s90
	s_add_u32 s76, s26, s89
	s_addc_u32 s77, s27, 0
	s_lshl_b32 s89, s86, 21
	s_lshl_b32 s90, s87, 17
	s_add_u32 s89, s89, s90
	s_lshl_b32 s90, s88, 7
	s_add_u32 s89, s89, s90
	s_add_u32 s78, s28, s89
	s_addc_u32 s79, s29, 0
	s_movk_i32 s80, 0x1000
.Lpo_dec0:
	v_mad_u32_u24 v72, v22, s80, v0
	s_lshl_b32 s0, s80, 4
	global_load_dwordx4 v[4:7], v72, s[76:77] nt
	s_add_u32 s76, s76, s0
	s_addc_u32 s77, s77, 0
	global_load_dwordx4 v[8:11], v72, s[76:77] nt
	s_add_u32 s76, s76, s0
	s_addc_u32 s77, s77, 0
	global_load_dwordx4 v[12:15], v72, s[76:77] nt
	s_add_u32 s76, s76, s0
	s_addc_u32 s77, s77, 0
	global_load_dwordx4 v[16:19], v72, s[76:77] nt
	s_add_i32 s1, s5, 0x1c0
	s_movk_i32 s86, 0x3c0
	s_cmpk_lt_u32 s1, 0x2c0
	s_cselect_b32 s86, 0x2c0, s86
	s_add_i32 s1, s1, s86
	s_cmpk_gt_i32 s1, 0x57f
	s_cbranch_scc1 .Lpo_out1
	s_mul_hi_i32 s86, s1, 0x2e8ba2e9
	s_ashr_i32 s86, s86, 7
	s_mul_i32 s87, s86, 0x2c0
	s_sub_i32 s87, s1, s87
	s_mul_i32 s88, s87, 0xba3
	s_lshr_b32 s88, s88, 17
	s_mul_i32 s89, s88, 44
	s_sub_i32 s87, s87, s89
	s_mul_i32 s89, s86, 0xb00000
	s_mul_i32 s90, s88, 0xb0000
	s_add_u32 s89, s89, s90
	s_lshl_b32 s90, s87, 8
	s_add_u32 s89, s89, s90
	s_add_u32 s82, s24, s89
	s_addc_u32 s83, s25, 0
	s_sub_i32 s90, s87, 20
	s_cmp_gt_u32 s90, 15
	s_cbranch_scc1 .Lpo_nr1
	s_and_b32 s91, s87, 3
	s_lshr_b32 s90, s90, 2
	s_lshl_b32 s90, s90, 3
	s_lshr_b32 s90, 0x1d15141c, s90
	s_and_b32 s90, s90, 0xff
	s_lshl_b32 s91, s91, 1
	s_add_i32 s87, s90, s91
.Lpo_nr1:
	s_mul_i32 s89, s86, 0x580000
	s_lshl_b32 s90, s87, 17
	s_add_u32 s89, s89, s90
	s_lshl_b32 s90, s88, 7
	s_add_u32 s89, s89, s90
	s_add_u32 s84, s30, s89
	s_addc_u32 s85, s31, 0
	s_movk_i32 s81, 0x2c00
	s_branch .Lpo_dec1
.Lpo_out1:
	s_add_i32 s87, s1, 0xfffffa80
	s_lshr_b32 s86, s87, 8
	s_bfe_u32 s88, s87, 0x40004
	s_and_b32 s87, s87, 15
	s_lshl_b32 s89, s86, 22
	s_lshl_b32 s90, s88, 18
	s_add_u32 s89, s89, s90
	s_lshl_b32 s90, s87, 8
	s_add_u32 s89, s89, s90
	s_add_u32 s82, s26, s89
	s_addc_u32 s83, s27, 0
	s_lshl_b32 s89, s86, 21
	s_lshl_b32 s90, s87, 17
	s_add_u32 s89, s89, s90
	s_lshl_b32 s90, s88, 7
	s_add_u32 s89, s89, s90
	s_add_u32 s84, s28, s89
	s_addc_u32 s85, s29, 0
	s_movk_i32 s81, 0x1000
.Lpo_dec1:
	v_mad_u32_u24 v73, v22, s81, v0
	s_lshl_b32 s0, s81, 4
	global_load_dwordx4 v[208:211], v73, s[82:83] nt
	s_add_u32 s82, s82, s0
	s_addc_u32 s83, s83, 0
	global_load_dwordx4 v[212:215], v73, s[82:83] nt
	s_add_u32 s82, s82, s0
	s_addc_u32 s83, s83, 0
	global_load_dwordx4 v[216:219], v73, s[82:83] nt
	s_add_u32 s82, s82, s0
	s_addc_u32 s83, s83, 0
	global_load_dwordx4 v[220:223], v73, s[82:83] nt
	s_add_i32 s1, s5, 0x380
	s_cmpk_gt_u32 s1, 0x3bf
	s_cbranch_scc1 .Lpo_dummy
	s_movk_i32 s86, 0x3c0
	s_cmpk_lt_u32 s1, 0x2c0
	s_cselect_b32 s86, 0x2c0, s86
	s_add_i32 s1, s1, s86
	s_cmpk_gt_i32 s1, 0x57f
	s_cbranch_scc1 .Lpo_out2
	s_mul_hi_i32 s86, s1, 0x2e8ba2e9
	s_ashr_i32 s86, s86, 7
	s_mul_i32 s87, s86, 0x2c0
	s_sub_i32 s87, s1, s87
	s_mul_i32 s88, s87, 0xba3
	s_lshr_b32 s88, s88, 17
	s_mul_i32 s89, s88, 44
	s_sub_i32 s87, s87, s89
	s_mul_i32 s89, s86, 0xb00000
	s_mul_i32 s90, s88, 0xb0000
	s_add_u32 s89, s89, s90
	s_lshl_b32 s90, s87, 8
	s_add_u32 s89, s89, s90
	s_add_u32 s20, s24, s89
	s_addc_u32 s21, s25, 0
	s_sub_i32 s90, s87, 20
	s_cmp_gt_u32 s90, 15
	s_cbranch_scc1 .Lpo_nr2
	s_and_b32 s91, s87, 3
	s_lshr_b32 s90, s90, 2
	s_lshl_b32 s90, s90, 3
	s_lshr_b32 s90, 0x1d15141c, s90
	s_and_b32 s90, s90, 0xff
	s_lshl_b32 s91, s91, 1
	s_add_i32 s87, s90, s91
.Lpo_nr2:
	s_mul_i32 s89, s86, 0x580000
	s_lshl_b32 s90, s87, 17
	s_add_u32 s89, s89, s90
	s_lshl_b32 s90, s88, 7
	s_add_u32 s89, s89, s90
	s_add_u32 s22, s30, s89
	s_addc_u32 s23, s31, 0
	s_movk_i32 s16, 0x2c00
	s_branch .Lpo_dec2
.Lpo_out2:
	s_add_i32 s87, s1, 0xfffffa80
	s_lshr_b32 s86, s87, 8
	s_bfe_u32 s88, s87, 0x40004
	s_and_b32 s87, s87, 15
	s_lshl_b32 s89, s86, 22
	s_lshl_b32 s90, s88, 18
	s_add_u32 s89, s89, s90
	s_lshl_b32 s90, s87, 8
	s_add_u32 s89, s89, s90
	s_add_u32 s20, s26, s89
	s_addc_u32 s21, s27, 0
	s_lshl_b32 s89, s86, 21
	s_lshl_b32 s90, s87, 17
	s_add_u32 s89, s89, s90
	s_lshl_b32 s90, s88, 7
	s_add_u32 s89, s89, s90
	s_add_u32 s22, s28, s89
	s_addc_u32 s23, s29, 0
	s_movk_i32 s16, 0x1000
	s_branch .Lpo_dec2
.Lpo_dummy:
	s_mov_b32 s20, s24
	s_mov_b32 s21, s25
	s_movk_i32 s16, 0x2c00
	s_mov_b32 s3, 0
	s_branch .Lpo_ldl
.Lpo_dec2:
	s_mov_b32 s3, 1
.Lpo_ldl:
	v_mad_u32_u24 v78, v22, s16, v0
	s_lshl_b32 s0, s16, 4
	global_load_dwordx4 v[224:227], v78, s[20:21] nt
	s_add_u32 s20, s20, s0
	s_addc_u32 s21, s21, 0
	global_load_dwordx4 v[228:231], v78, s[20:21] nt
	s_add_u32 s20, s20, s0
	s_addc_u32 s21, s21, 0
	global_load_dwordx4 v[232:235], v78, s[20:21] nt
	s_add_u32 s20, s20, s0
	s_addc_u32 s21, s21, 0
	global_load_dwordx4 v[236:239], v78, s[20:21] nt
	s_barrier
	s_waitcnt vmcnt(11)
	ds_write2_b32 v25, v4, v5 offset1:1
	ds_write2_b32 v25, v6, v7 offset0:2 offset1:3
	s_waitcnt vmcnt(10)
	ds_write2_b32 v26, v8, v9 offset1:1
	ds_write2_b32 v27, v10, v11 offset1:1
	s_waitcnt vmcnt(9)
	ds_write2_b32 v28, v12, v13 offset1:1
	ds_write2_b32 v29, v14, v15 offset1:1
	s_waitcnt vmcnt(8)
	ds_write2_b32 v30, v16, v17 offset1:1
	ds_write2_b32 v31, v18, v19 offset1:1
	s_waitcnt lgkmcnt(0)
	s_barrier
	ds_read2_b32 v[4:5], v24 offset1:65
	ds_read2_b32 v[6:7], v24 offset0:130 offset1:195
	ds_read2_b32 v[8:9], v83 offset0:4 offset1:69
	ds_read2_b32 v[10:11], v83 offset0:134 offset1:199
	ds_read2_b32 v[12:13], v84 offset0:8 offset1:73
	ds_read2_b32 v[14:15], v84 offset0:138 offset1:203
	ds_read2_b32 v[16:17], v85 offset0:12 offset1:77
	ds_read2_b32 v[18:19], v85 offset0:142 offset1:207
	s_waitcnt lgkmcnt(7)
	v_cvt_pk_bf16_f32 v4, v4, v5
	s_waitcnt lgkmcnt(6)
	v_cvt_pk_bf16_f32 v5, v6, v7
	s_waitcnt lgkmcnt(5)
	v_cvt_pk_bf16_f32 v6, v8, v9
	s_waitcnt lgkmcnt(4)
	v_cvt_pk_bf16_f32 v7, v10, v11
	s_waitcnt lgkmcnt(3)
	v_cvt_pk_bf16_f32 v8, v12, v13
	s_waitcnt lgkmcnt(2)
	v_cvt_pk_bf16_f32 v9, v14, v15
	s_waitcnt lgkmcnt(1)
	v_cvt_pk_bf16_f32 v10, v16, v17
	s_waitcnt lgkmcnt(0)
	v_cvt_pk_bf16_f32 v11, v18, v19
	global_store_dwordx4 v82, v[4:7], s[78:79]
	global_store_dwordx4 v82, v[8:11], s[78:79] offset:16
	s_barrier
	s_waitcnt vmcnt(9)
	ds_write2_b32 v25, v208, v209 offset1:1
	ds_write2_b32 v25, v210, v211 offset0:2 offset1:3
	s_waitcnt vmcnt(8)
	ds_write2_b32 v26, v212, v213 offset1:1
	ds_write2_b32 v27, v214, v215 offset1:1
	s_waitcnt vmcnt(7)
	ds_write2_b32 v28, v216, v217 offset1:1
	ds_write2_b32 v29, v218, v219 offset1:1
	s_waitcnt vmcnt(6)
	ds_write2_b32 v30, v220, v221 offset1:1
	ds_write2_b32 v31, v222, v223 offset1:1
	s_waitcnt lgkmcnt(0)
	s_barrier
	ds_read2_b32 v[4:5], v24 offset1:65
	ds_read2_b32 v[6:7], v24 offset0:130 offset1:195
	ds_read2_b32 v[8:9], v83 offset0:4 offset1:69
	ds_read2_b32 v[10:11], v83 offset0:134 offset1:199
	ds_read2_b32 v[12:13], v84 offset0:8 offset1:73
	ds_read2_b32 v[14:15], v84 offset0:138 offset1:203
	ds_read2_b32 v[16:17], v85 offset0:12 offset1:77
	ds_read2_b32 v[18:19], v85 offset0:142 offset1:207
	s_waitcnt lgkmcnt(7)
	v_cvt_pk_bf16_f32 v4, v4, v5
	s_waitcnt lgkmcnt(6)
	v_cvt_pk_bf16_f32 v5, v6, v7
	s_waitcnt lgkmcnt(5)
	v_cvt_pk_bf16_f32 v6, v8, v9
	s_waitcnt lgkmcnt(4)
	v_cvt_pk_bf16_f32 v7, v10, v11
	s_waitcnt lgkmcnt(3)
	v_cvt_pk_bf16_f32 v8, v12, v13
	s_waitcnt lgkmcnt(2)
	v_cvt_pk_bf16_f32 v9, v14, v15
	s_waitcnt lgkmcnt(1)
	v_cvt_pk_bf16_f32 v10, v16, v17
	s_waitcnt lgkmcnt(0)
	v_cvt_pk_bf16_f32 v11, v18, v19
	global_store_dwordx4 v82, v[4:7], s[84:85]
	global_store_dwordx4 v82, v[8:11], s[84:85] offset:16
	s_cmp_eq_u32 s3, 0
	s_cbranch_scc1 .Lpo_done
	s_barrier
	s_waitcnt vmcnt(7)
	ds_write2_b32 v25, v224, v225 offset1:1
	ds_write2_b32 v25, v226, v227 offset0:2 offset1:3
	s_waitcnt vmcnt(6)
	ds_write2_b32 v26, v228, v229 offset1:1
	ds_write2_b32 v27, v230, v231 offset1:1
	s_waitcnt vmcnt(5)
	ds_write2_b32 v28, v232, v233 offset1:1
	ds_write2_b32 v29, v234, v235 offset1:1
	s_waitcnt vmcnt(4)
	ds_write2_b32 v30, v236, v237 offset1:1
	ds_write2_b32 v31, v238, v239 offset1:1
	s_waitcnt lgkmcnt(0)
	s_barrier
	ds_read2_b32 v[4:5], v24 offset1:65
	ds_read2_b32 v[6:7], v24 offset0:130 offset1:195
	ds_read2_b32 v[8:9], v83 offset0:4 offset1:69
	ds_read2_b32 v[10:11], v83 offset0:134 offset1:199
	ds_read2_b32 v[12:13], v84 offset0:8 offset1:73
	ds_read2_b32 v[14:15], v84 offset0:138 offset1:203
	ds_read2_b32 v[16:17], v85 offset0:12 offset1:77
	ds_read2_b32 v[18:19], v85 offset0:142 offset1:207
	s_waitcnt lgkmcnt(7)
	v_cvt_pk_bf16_f32 v4, v4, v5
	s_waitcnt lgkmcnt(6)
	v_cvt_pk_bf16_f32 v5, v6, v7
	s_waitcnt lgkmcnt(5)
	v_cvt_pk_bf16_f32 v6, v8, v9
	s_waitcnt lgkmcnt(4)
	v_cvt_pk_bf16_f32 v7, v10, v11
	s_waitcnt lgkmcnt(3)
	v_cvt_pk_bf16_f32 v8, v12, v13
	s_waitcnt lgkmcnt(2)
	v_cvt_pk_bf16_f32 v9, v14, v15
	s_waitcnt lgkmcnt(1)
	v_cvt_pk_bf16_f32 v10, v16, v17
	s_waitcnt lgkmcnt(0)
	v_cvt_pk_bf16_f32 v11, v18, v19
	global_store_dwordx4 v82, v[4:7], s[22:23]
	global_store_dwordx4 v82, v[8:11], s[22:23] offset:16
.Lpo_done:
.Lpo_skip:
	s_waitcnt vmcnt(0)
	s_barrier
	s_mov_b64 s[12:13], exec
	v_readlane_b32 s2, v207, 0
	v_readlane_b32 s3, v207, 1
	s_and_b64 s[2:3], s[12:13], s[2:3]
	s_mov_b64 exec, s[2:3]
	s_cbranch_execz .LBB0_177
	s_waitcnt vmcnt(0) expcnt(0) lgkmcnt(0)
	ds_read_b32 v2, v140
	ds_read_b32 v0, v141
	s_waitcnt lgkmcnt(1)
	v_cmp_ne_u32_e32 vcc, 0, v2
	s_cbranch_vccnz .LBB0_684
	v_readlane_b32 s16, v207, 52
	v_readlane_b32 s17, v207, 53
	s_load_dwordx2 s[2:3], s[16:17], 0x4
	v_readlane_b32 s4, v205, 18
	s_mov_b32 s38, 1
	s_waitcnt lgkmcnt(0)
	s_mul_i32 s18, s2, s4
	s_mul_i32 s18, s18, s3
	s_branch .LBB0_672
